# counted lgkmcnt: WIN QK^T K-fragment LDS reads pipelined 3 deep too
# speedup vs baseline: 1.0138x; 1.0106x over previous
; #define LAS __attribute__((address_space(3)))
; #define MFMA32(a, b, c) __builtin_amdgcn_mfma_f32_32x32x16_bf16((a), (b), (c), 0, 0, 0)
; template <int MODE> DI void attn_h1(AttnCtx& c, const bf16x8 (&q)[8], f32x16 (&o)[4], f32x16& s0, f32x16& s1, ldsp lds, int kbuf, int bbuf, int tj, int lane) {
;     ...
;             ldsp kl = lds + kbuf + r32 * KPITCH + h * 16;
; #pragma unroll
;             for (int e = 0; e < 16; ++e) { s0[e] = 0.f; s1[e] = 0.f; }
; #pragma unroll
;             for (int s = 0; s < 8; ++s) {
;                 const bf16x8 ka = *(const LAS bf16x8*)(kl + s * 32), kb = *(const LAS bf16x8*)(kl + 32 * KPITCH + s * 32);
;                 s0 = MFMA32(ka, q[s], s0); s1 = MFMA32(kb, q[s], s1);
;                 if (s == 3) asm volatile("" ::: "memory");
;             }
;     ...
;                 } else {
;                     const float a0 = selbit ? -c.slope2 * dbase : NINF;
; #pragma unroll
;                     for (int e = 0; e < 16; ++e) {
;                         s0[e] = fmaf(c.slope2, (float)(PS * (8 * (e >> 2) + (e & 3))), s0[e] + a0);
;                         s1[e] = fmaf(c.slope2, (float)(PS * (32 + 8 * (e >> 2) + (e & 3))), s1[e] + a0);
;                     }
;                 }
.LBB0_1066:
	s_and_b32 s19, s18, 1
	s_mul_i32 s2, s19, 0x4400
	v_add_u32_e32 v148, s2, v0
	ds_read_b128 v[66:69], v148 offset:8704
	ds_read_b128 v[70:73], v148
	ds_read_b128 v[160:163], v148 offset:32
	ds_read_b128 v[164:167], v148 offset:8736
	ds_read_b128 v[168:171], v148 offset:64
	ds_read_b128 v[172:175], v148 offset:8768
	ds_read_b128 v[178:181], v148 offset:96
	ds_read_b128 v[182:185], v148 offset:8800
	v_cvt_f32_i32_e32 v176, v198
	s_mov_b64 s[2:3], -1
	s_waitcnt lgkmcnt(6)
	v_mfma_f32_32x32x16_bf16 v[82:97], v[70:73], v[98:101], 0
	s_cmp_lg_u32 s18, 8
	v_mfma_f32_32x32x16_bf16 v[66:81], v[66:69], v[98:101], 0
	s_waitcnt lgkmcnt(4)
	v_mfma_f32_32x32x16_bf16 v[82:97], v[160:163], v[102:105], v[82:97]
	v_mfma_f32_32x32x16_bf16 v[66:81], v[164:167], v[102:105], v[66:81]
	ds_read_b128 v[160:163], v148 offset:128
	ds_read_b128 v[164:167], v148 offset:8832
	s_waitcnt lgkmcnt(4)
	v_mfma_f32_32x32x16_bf16 v[82:97], v[168:171], v[106:109], v[82:97]
	v_mfma_f32_32x32x16_bf16 v[66:81], v[172:175], v[106:109], v[66:81]
	ds_read_b128 v[168:171], v148 offset:160
	ds_read_b128 v[172:175], v148 offset:8864
	s_waitcnt lgkmcnt(4)
	v_mfma_f32_32x32x16_bf16 v[82:97], v[178:181], v[110:113], v[82:97]
	v_mfma_f32_32x32x16_bf16 v[66:81], v[182:185], v[110:113], v[66:81]
	ds_read_b128 v[178:181], v148 offset:192
	ds_read_b128 v[182:185], v148 offset:8896
	s_waitcnt lgkmcnt(4)
	v_mfma_f32_32x32x16_bf16 v[82:97], v[160:163], v[114:117], v[82:97]
	v_mfma_f32_32x32x16_bf16 v[66:81], v[164:167], v[114:117], v[66:81]
	ds_read_b128 v[160:163], v148 offset:224
	ds_read_b128 v[164:167], v148 offset:8928
	s_waitcnt lgkmcnt(4)
	v_mfma_f32_32x32x16_bf16 v[82:97], v[168:171], v[118:121], v[82:97]
	v_mfma_f32_32x32x16_bf16 v[66:81], v[172:175], v[118:121], v[66:81]
	s_waitcnt lgkmcnt(2)
	v_mfma_f32_32x32x16_bf16 v[82:97], v[178:181], v[122:125], v[82:97]
	v_mfma_f32_32x32x16_bf16 v[66:81], v[182:185], v[122:125], v[66:81]
	s_waitcnt lgkmcnt(0)
	v_mfma_f32_32x32x16_bf16 v[82:97], v[160:163], v[126:129], v[82:97]
	v_mfma_f32_32x32x16_bf16 v[66:81], v[164:167], v[126:129], v[66:81]
	s_nop 10
	v_fma_f32 v201, -v146, v176, v82
	s_cbranch_scc0 .LBB0_1068
	v_mul_f32_e64 v184, -v146, v176
	v_fma_f32 v148, -v146, v176, v83
	s_mov_b32 s2, 0x42000000
	v_add_f32_e32 v177, v146, v148
	v_add_f32_e64 v148, v184, v66
	v_add_f32_e64 v149, v184, v67
	s_mov_b32 s3, 0x42040000
	v_fma_f32 v154, v146, s2, v148
	v_fma_f32 v155, v147, s3, v149
	s_mov_b32 s2, 2.0
	v_add_f32_e64 v148, v184, v84
	v_add_f32_e64 v149, v184, v85
	s_mov_b32 s3, 0x40400000
	v_fma_f32 v148, v146, s2, v148
	v_fma_f32 v149, v147, s3, v149
	s_mov_b32 s2, 0x42080000
	v_add_f32_e64 v160, v184, v68
	v_add_f32_e64 v161, v184, v69
	s_mov_b32 s3, 0x420c0000
	v_fma_f32 v162, v146, s2, v160
	v_fma_f32 v163, v147, s3, v161
	s_mov_b32 s2, 0x41000000
	v_add_f32_e64 v160, v184, v86
	v_add_f32_e64 v161, v184, v87
	s_mov_b32 s3, 0x41100000
	v_fma_f32 v160, v146, s2, v160
	v_fma_f32 v161, v147, s3, v161
	s_mov_b32 s2, 0x42200000
	v_add_f32_e64 v164, v184, v70
	v_add_f32_e64 v165, v184, v71
	s_mov_b32 s3, 0x42240000
	v_fma_f32 v164, v146, s2, v164
	v_fma_f32 v165, v147, s3, v165
	s_mov_b32 s2, 0x41200000
	v_add_f32_e64 v166, v184, v88
	v_add_f32_e64 v167, v184, v89
	s_mov_b32 s3, 0x41300000
	v_fma_f32 v166, v146, s2, v166
	v_fma_f32 v167, v147, s3, v167
	s_mov_b32 s2, 0x42280000
	v_add_f32_e64 v168, v184, v72
	v_add_f32_e64 v169, v184, v73
	s_mov_b32 s3, 0x422c0000
	v_fma_f32 v168, v146, s2, v168
	v_fma_f32 v169, v147, s3, v169
	s_mov_b32 s2, 0x41800000
	v_add_f32_e64 v170, v184, v90
	v_add_f32_e64 v171, v184, v91
	s_mov_b32 s3, 0x41880000
	v_fma_f32 v170, v146, s2, v170
	v_fma_f32 v171, v147, s3, v171
	s_mov_b32 s2, 0x42400000
	v_add_f32_e64 v172, v184, v74
	v_add_f32_e64 v173, v184, v75
	s_mov_b32 s3, 0x42440000
	v_fma_f32 v172, v146, s2, v172
	v_fma_f32 v173, v147, s3, v173
	s_mov_b32 s2, 0x41900000
	v_add_f32_e64 v174, v184, v92
	v_add_f32_e64 v175, v184, v93
	s_mov_b32 s3, 0x41980000
	v_fma_f32 v174, v146, s2, v174
	v_fma_f32 v175, v147, s3, v175
	s_mov_b32 s2, 0x42480000
	v_add_f32_e64 v178, v184, v76
	v_add_f32_e64 v179, v184, v77
	s_mov_b32 s3, 0x424c0000
	v_fma_f32 v178, v146, s2, v178
	v_fma_f32 v179, v147, s3, v179
	s_mov_b32 s2, 0x41c00000
	v_add_f32_e64 v180, v184, v94
	v_add_f32_e64 v181, v184, v95
	s_mov_b32 s3, 0x41c80000
	v_fma_f32 v180, v146, s2, v180
	v_fma_f32 v181, v147, s3, v181
	s_mov_b32 s2, 0x42600000
	v_add_f32_e64 v182, v184, v78
	v_add_f32_e64 v183, v184, v79
	s_mov_b32 s3, 0x42640000
	v_fma_f32 v182, v146, s2, v182
	v_fma_f32 v183, v147, s3, v183
	s_mov_b32 s2, 0x41d00000
	v_fma_f32 v199, -v146, v176, v80
	v_add_f32_e64 v185, v184, v97
	v_add_f32_e64 v184, v184, v96
	s_mov_b32 s3, 0x41d80000
	v_fma_f32 v200, -v146, v176, v81
	v_fma_f32 v82, 0, v146, v201
	v_fmac_f32_e32 v199, 0x42680000, v146
	v_fma_f32 v184, v146, s2, v184
	v_fma_f32 v185, v147, s3, v185
	v_fmac_f32_e32 v200, 0x426c0000, v146
	s_mov_b64 s[2:3], 0
